# v5 + single s_waitcnt per scan step (3 register sets / distance-2 LDS prefetch in rwkv, deeper prefetch in ssd)
# speedup vs baseline: 1.0345x; 1.0123x over previous
; __device__ __forceinline__ void ssd_scan_unit(CP p, int l, int u, char* smem) {
;     ...
; #pragma unroll 2
;     for (int s = 0; s < 16; ++s) {
;       const float* sb = cb + (s + 1) * SST;
;       const float4 B0n = *reinterpret_cast<const float4*>(sb + j * 4), B1n = *reinterpret_cast<const float4*>(sb + 64 + j * 4);
;       const float4 C0n = *reinterpret_cast<const float4*>(sb + 128 + j * 4), C1n = *reinterpret_cast<const float4*>(sb + 192 + j * 4);
;       const float xdtn = sb[256 + prow], xrn = sb[272 + prow], an = sb[288];
;       __builtin_amdgcn_sched_barrier(0);
;       hs[0] = fmaf(a, hs[0], xdt * B0.x); hs[1] = fmaf(a, hs[1], xdt * B0.y); hs[2] = fmaf(a, hs[2], xdt * B0.z); hs[3] = fmaf(a, hs[3], xdt * B0.w);
;       hs[4] = fmaf(a, hs[4], xdt * B1.x); hs[5] = fmaf(a, hs[5], xdt * B1.y); hs[6] = fmaf(a, hs[6], xdt * B1.z); hs[7] = fmaf(a, hs[7], xdt * B1.w);
;       float y = hs[0] * C0.x + hs[1] * C0.y + hs[2] * C0.z + hs[3] * C0.w + hs[4] * C1.x + hs[5] * C1.y + hs[6] * C1.z + hs[7] * C1.w;
;       y = allreduce16(y);
;       y = fmaf(Dh, xr, y);
;       if (j == s) ykeep = y;
;       B0 = B0n; B1 = B1n; C0 = C0n; C1 = C1n; xdt = xdtn; xr = xrn; a = an;
;     }
.LBB0_546:
	s_lshl_b32 s5, s4, 4
	s_and_b32 s12, s5, 16
	s_mulk_i32 s12, 0x4a0
	s_add_i32 s12, s63, s12
	s_movk_i32 s13, 0x4a0
	v_lshl_add_u32 v84, v56, 2, s12
	v_lshl_add_u32 v85, v24, 2, s12
	v_mov_b32_e32 v86, s12
	v_add_u32_e32 v85, 0x400, v85
	s_nop 0
	v_mad_u32_u24 v87, v44, s13, v85
	ds_read_b128 v[90:93], v84 offset:0
	ds_read_b32 v106, v85 offset:0
	ds_read_b128 v[94:97], v84 offset:256
	ds_read_b32 v108, v86 offset:1152
	ds_read_b128 v[98:101], v84 offset:512
	ds_read_b128 v[102:105], v84 offset:768
	ds_read_b128 v[112:115], v84 offset:1184
	ds_read_b32 v128, v85 offset:1184
	ds_read_b128 v[116:119], v84 offset:1440
	ds_read_b32 v130, v86 offset:2336
	ds_read_b128 v[120:123], v84 offset:1696
	ds_read_b128 v[124:127], v84 offset:1952
	ds_read_b32 v186, v87 offset:64
	s_waitcnt lgkmcnt(10)
	v_pk_mul_f32 v[176:177], v[90:91], v[106:107] op_sel_hi:[1,0]
	v_pk_mul_f32 v[178:179], v[92:93], v[106:107] op_sel_hi:[1,0]
	v_pk_mul_f32 v[180:181], v[94:95], v[106:107] op_sel_hi:[1,0]
	v_pk_mul_f32 v[182:183], v[96:97], v[106:107] op_sel_hi:[1,0]
	ds_read_b128 v[90:93], v84 offset:2368
	ds_read_b32 v106, v85 offset:2368
	ds_read_b128 v[94:97], v84 offset:2624
	s_waitcnt lgkmcnt(7)
	v_pk_fma_f32 v[32:33], v[108:109], v[32:33], v[176:177] op_sel_hi:[0,1,1]
	v_pk_fma_f32 v[38:39], v[108:109], v[38:39], v[178:179] op_sel_hi:[0,1,1]
	v_pk_fma_f32 v[36:37], v[108:109], v[36:37], v[180:181] op_sel_hi:[0,1,1]
	v_pk_fma_f32 v[34:35], v[108:109], v[34:35], v[182:183] op_sel_hi:[0,1,1]
	v_pk_mul_f32 v[184:185], v[32:33], v[98:99]
	v_pk_mul_f32 v[176:177], v[112:113], v[128:129] op_sel_hi:[1,0]
	v_pk_fma_f32 v[184:185], v[38:39], v[100:101], v[184:185]
	v_pk_mul_f32 v[178:179], v[114:115], v[128:129] op_sel_hi:[1,0]
	v_pk_fma_f32 v[184:185], v[36:37], v[102:103], v[184:185]
	v_pk_mul_f32 v[180:181], v[116:117], v[128:129] op_sel_hi:[1,0]
	v_pk_fma_f32 v[184:185], v[34:35], v[104:105], v[184:185]
	v_pk_mul_f32 v[182:183], v[118:119], v[128:129] op_sel_hi:[1,0]
	v_add_f32_e32 v160, v184, v185
	ds_read_b128 v[112:115], v84 offset:3552
	ds_read_b32 v128, v85 offset:3552
	ds_read_b128 v[116:119], v84 offset:3808
	ds_read_b32 v108, v86 offset:3520
	ds_read_b128 v[98:101], v84 offset:2880
	ds_read_b128 v[102:105], v84 offset:3136
	s_waitcnt lgkmcnt(6)
	v_pk_fma_f32 v[32:33], v[130:131], v[32:33], v[176:177] op_sel_hi:[0,1,1]
	v_pk_fma_f32 v[38:39], v[130:131], v[38:39], v[178:179] op_sel_hi:[0,1,1]
	v_pk_fma_f32 v[36:37], v[130:131], v[36:37], v[180:181] op_sel_hi:[0,1,1]
	v_pk_fma_f32 v[34:35], v[130:131], v[34:35], v[182:183] op_sel_hi:[0,1,1]
	v_pk_mul_f32 v[184:185], v[32:33], v[120:121]
	v_pk_mul_f32 v[176:177], v[90:91], v[106:107] op_sel_hi:[1,0]
	v_pk_fma_f32 v[184:185], v[38:39], v[122:123], v[184:185]
	v_pk_mul_f32 v[178:179], v[92:93], v[106:107] op_sel_hi:[1,0]
	v_pk_fma_f32 v[184:185], v[36:37], v[124:125], v[184:185]
	v_pk_mul_f32 v[180:181], v[94:95], v[106:107] op_sel_hi:[1,0]
	v_pk_fma_f32 v[184:185], v[34:35], v[126:127], v[184:185]
	v_pk_mul_f32 v[182:183], v[96:97], v[106:107] op_sel_hi:[1,0]
	v_add_f32_e32 v161, v184, v185
	ds_read_b128 v[90:93], v84 offset:4736
	ds_read_b32 v106, v85 offset:4736
	ds_read_b128 v[94:97], v84 offset:4992
	ds_read_b32 v130, v86 offset:4704
	ds_read_b128 v[120:123], v84 offset:4064
	ds_read_b128 v[124:127], v84 offset:4320
	s_waitcnt lgkmcnt(6)
	v_pk_fma_f32 v[32:33], v[108:109], v[32:33], v[176:177] op_sel_hi:[0,1,1]
	v_pk_fma_f32 v[38:39], v[108:109], v[38:39], v[178:179] op_sel_hi:[0,1,1]
	v_pk_fma_f32 v[36:37], v[108:109], v[36:37], v[180:181] op_sel_hi:[0,1,1]
	v_pk_fma_f32 v[34:35], v[108:109], v[34:35], v[182:183] op_sel_hi:[0,1,1]
	v_pk_mul_f32 v[184:185], v[32:33], v[98:99]
	v_pk_mul_f32 v[176:177], v[112:113], v[128:129] op_sel_hi:[1,0]
	v_pk_fma_f32 v[184:185], v[38:39], v[100:101], v[184:185]
	v_pk_mul_f32 v[178:179], v[114:115], v[128:129] op_sel_hi:[1,0]
	v_pk_fma_f32 v[184:185], v[36:37], v[102:103], v[184:185]
	v_pk_mul_f32 v[180:181], v[116:117], v[128:129] op_sel_hi:[1,0]
	v_pk_fma_f32 v[184:185], v[34:35], v[104:105], v[184:185]
	v_pk_mul_f32 v[182:183], v[118:119], v[128:129] op_sel_hi:[1,0]
	v_add_f32_e32 v162, v184, v185
	ds_read_b128 v[112:115], v84 offset:5920
	ds_read_b32 v128, v85 offset:5920
	ds_read_b128 v[116:119], v84 offset:6176
	ds_read_b32 v108, v86 offset:5888
	ds_read_b128 v[98:101], v84 offset:5248
	ds_read_b128 v[102:105], v84 offset:5504
	s_waitcnt lgkmcnt(6)
	v_pk_fma_f32 v[32:33], v[130:131], v[32:33], v[176:177] op_sel_hi:[0,1,1]
	v_pk_fma_f32 v[38:39], v[130:131], v[38:39], v[178:179] op_sel_hi:[0,1,1]
	v_pk_fma_f32 v[36:37], v[130:131], v[36:37], v[180:181] op_sel_hi:[0,1,1]
	v_pk_fma_f32 v[34:35], v[130:131], v[34:35], v[182:183] op_sel_hi:[0,1,1]
	v_pk_mul_f32 v[184:185], v[32:33], v[120:121]
	v_pk_mul_f32 v[176:177], v[90:91], v[106:107] op_sel_hi:[1,0]
	v_pk_fma_f32 v[184:185], v[38:39], v[122:123], v[184:185]
	v_pk_mul_f32 v[178:179], v[92:93], v[106:107] op_sel_hi:[1,0]
	v_pk_fma_f32 v[184:185], v[36:37], v[124:125], v[184:185]
	v_pk_mul_f32 v[180:181], v[94:95], v[106:107] op_sel_hi:[1,0]
	v_pk_fma_f32 v[184:185], v[34:35], v[126:127], v[184:185]
	v_pk_mul_f32 v[182:183], v[96:97], v[106:107] op_sel_hi:[1,0]
	v_add_f32_e32 v163, v184, v185
	ds_read_b128 v[90:93], v84 offset:7104
	ds_read_b32 v106, v85 offset:7104
	ds_read_b128 v[94:97], v84 offset:7360
	ds_read_b32 v130, v86 offset:7072
	ds_read_b128 v[120:123], v84 offset:6432
	ds_read_b128 v[124:127], v84 offset:6688
	s_waitcnt lgkmcnt(6)
; __device__ __forceinline__ void ssd_scan_unit(CP p, int l, int u, char* smem) {
;     ...
; #pragma unroll 2
;     for (int s = 0; s < 16; ++s) {
;       const float* sb = cb + (s + 1) * SST;
;       const float4 B0n = *reinterpret_cast<const float4*>(sb + j * 4), B1n = *reinterpret_cast<const float4*>(sb + 64 + j * 4);
;       const float4 C0n = *reinterpret_cast<const float4*>(sb + 128 + j * 4), C1n = *reinterpret_cast<const float4*>(sb + 192 + j * 4);
;       const float xdtn = sb[256 + prow], xrn = sb[272 + prow], an = sb[288];
;       __builtin_amdgcn_sched_barrier(0);
;       hs[0] = fmaf(a, hs[0], xdt * B0.x); hs[1] = fmaf(a, hs[1], xdt * B0.y); hs[2] = fmaf(a, hs[2], xdt * B0.z); hs[3] = fmaf(a, hs[3], xdt * B0.w);
;       hs[4] = fmaf(a, hs[4], xdt * B1.x); hs[5] = fmaf(a, hs[5], xdt * B1.y); hs[6] = fmaf(a, hs[6], xdt * B1.z); hs[7] = fmaf(a, hs[7], xdt * B1.w);
;       float y = hs[0] * C0.x + hs[1] * C0.y + hs[2] * C0.z + hs[3] * C0.w + hs[4] * C1.x + hs[5] * C1.y + hs[6] * C1.z + hs[7] * C1.w;
;       y = allreduce16(y);
;       y = fmaf(Dh, xr, y);
;       if (j == s) ykeep = y;
;       B0 = B0n; B1 = B1n; C0 = C0n; C1 = C1n; xdt = xdtn; xr = xrn; a = an;
;     }
	v_pk_fma_f32 v[32:33], v[108:109], v[32:33], v[176:177] op_sel_hi:[0,1,1]
	v_pk_fma_f32 v[38:39], v[108:109], v[38:39], v[178:179] op_sel_hi:[0,1,1]
	v_pk_fma_f32 v[36:37], v[108:109], v[36:37], v[180:181] op_sel_hi:[0,1,1]
	v_pk_fma_f32 v[34:35], v[108:109], v[34:35], v[182:183] op_sel_hi:[0,1,1]
	v_pk_mul_f32 v[184:185], v[32:33], v[98:99]
	v_pk_mul_f32 v[176:177], v[112:113], v[128:129] op_sel_hi:[1,0]
	v_pk_fma_f32 v[184:185], v[38:39], v[100:101], v[184:185]
	v_pk_mul_f32 v[178:179], v[114:115], v[128:129] op_sel_hi:[1,0]
	v_pk_fma_f32 v[184:185], v[36:37], v[102:103], v[184:185]
	v_pk_mul_f32 v[180:181], v[116:117], v[128:129] op_sel_hi:[1,0]
	v_pk_fma_f32 v[184:185], v[34:35], v[104:105], v[184:185]
	v_pk_mul_f32 v[182:183], v[118:119], v[128:129] op_sel_hi:[1,0]
	v_add_f32_e32 v164, v184, v185
	ds_read_b128 v[112:115], v84 offset:8288
	ds_read_b32 v128, v85 offset:8288
	ds_read_b128 v[116:119], v84 offset:8544
	ds_read_b32 v108, v86 offset:8256
	ds_read_b128 v[98:101], v84 offset:7616
	ds_read_b128 v[102:105], v84 offset:7872
	s_waitcnt lgkmcnt(6)
	v_pk_fma_f32 v[32:33], v[130:131], v[32:33], v[176:177] op_sel_hi:[0,1,1]
	v_pk_fma_f32 v[38:39], v[130:131], v[38:39], v[178:179] op_sel_hi:[0,1,1]
	v_pk_fma_f32 v[36:37], v[130:131], v[36:37], v[180:181] op_sel_hi:[0,1,1]
	v_pk_fma_f32 v[34:35], v[130:131], v[34:35], v[182:183] op_sel_hi:[0,1,1]
	v_pk_mul_f32 v[184:185], v[32:33], v[120:121]
	v_pk_mul_f32 v[176:177], v[90:91], v[106:107] op_sel_hi:[1,0]
	v_pk_fma_f32 v[184:185], v[38:39], v[122:123], v[184:185]
	v_pk_mul_f32 v[178:179], v[92:93], v[106:107] op_sel_hi:[1,0]
	v_pk_fma_f32 v[184:185], v[36:37], v[124:125], v[184:185]
	v_pk_mul_f32 v[180:181], v[94:95], v[106:107] op_sel_hi:[1,0]
	v_pk_fma_f32 v[184:185], v[34:35], v[126:127], v[184:185]
	v_pk_mul_f32 v[182:183], v[96:97], v[106:107] op_sel_hi:[1,0]
	v_add_f32_e32 v165, v184, v185
	ds_read_b128 v[90:93], v84 offset:9472
	ds_read_b32 v106, v85 offset:9472
	ds_read_b128 v[94:97], v84 offset:9728
	ds_read_b32 v130, v86 offset:9440
	ds_read_b128 v[120:123], v84 offset:8800
	ds_read_b128 v[124:127], v84 offset:9056
	s_waitcnt lgkmcnt(6)
	v_pk_fma_f32 v[32:33], v[108:109], v[32:33], v[176:177] op_sel_hi:[0,1,1]
	v_pk_fma_f32 v[38:39], v[108:109], v[38:39], v[178:179] op_sel_hi:[0,1,1]
	v_pk_fma_f32 v[36:37], v[108:109], v[36:37], v[180:181] op_sel_hi:[0,1,1]
	v_pk_fma_f32 v[34:35], v[108:109], v[34:35], v[182:183] op_sel_hi:[0,1,1]
	v_pk_mul_f32 v[184:185], v[32:33], v[98:99]
	v_pk_mul_f32 v[176:177], v[112:113], v[128:129] op_sel_hi:[1,0]
	v_pk_fma_f32 v[184:185], v[38:39], v[100:101], v[184:185]
	v_pk_mul_f32 v[178:179], v[114:115], v[128:129] op_sel_hi:[1,0]
	v_pk_fma_f32 v[184:185], v[36:37], v[102:103], v[184:185]
	v_pk_mul_f32 v[180:181], v[116:117], v[128:129] op_sel_hi:[1,0]
	v_pk_fma_f32 v[184:185], v[34:35], v[104:105], v[184:185]
	v_pk_mul_f32 v[182:183], v[118:119], v[128:129] op_sel_hi:[1,0]
	v_add_f32_e32 v166, v184, v185
	ds_read_b128 v[112:115], v84 offset:10656
	ds_read_b32 v128, v85 offset:10656
	ds_read_b128 v[116:119], v84 offset:10912
	ds_read_b32 v108, v86 offset:10624
	ds_read_b128 v[98:101], v84 offset:9984
	ds_read_b128 v[102:105], v84 offset:10240
	s_waitcnt lgkmcnt(6)
	v_pk_fma_f32 v[32:33], v[130:131], v[32:33], v[176:177] op_sel_hi:[0,1,1]
	v_pk_fma_f32 v[38:39], v[130:131], v[38:39], v[178:179] op_sel_hi:[0,1,1]
	v_pk_fma_f32 v[36:37], v[130:131], v[36:37], v[180:181] op_sel_hi:[0,1,1]
	v_pk_fma_f32 v[34:35], v[130:131], v[34:35], v[182:183] op_sel_hi:[0,1,1]
	v_pk_mul_f32 v[184:185], v[32:33], v[120:121]
	v_pk_mul_f32 v[176:177], v[90:91], v[106:107] op_sel_hi:[1,0]
	v_pk_fma_f32 v[184:185], v[38:39], v[122:123], v[184:185]
	v_pk_mul_f32 v[178:179], v[92:93], v[106:107] op_sel_hi:[1,0]
	v_pk_fma_f32 v[184:185], v[36:37], v[124:125], v[184:185]
	v_pk_mul_f32 v[180:181], v[94:95], v[106:107] op_sel_hi:[1,0]
	v_pk_fma_f32 v[184:185], v[34:35], v[126:127], v[184:185]
	v_pk_mul_f32 v[182:183], v[96:97], v[106:107] op_sel_hi:[1,0]
	v_add_f32_e32 v167, v184, v185
	ds_read_b128 v[90:93], v84 offset:11840
	ds_read_b32 v106, v85 offset:11840
	ds_read_b128 v[94:97], v84 offset:12096
	ds_read_b32 v130, v86 offset:11808
	ds_read_b128 v[120:123], v84 offset:11168
	ds_read_b128 v[124:127], v84 offset:11424
	s_waitcnt lgkmcnt(6)
	v_pk_fma_f32 v[32:33], v[108:109], v[32:33], v[176:177] op_sel_hi:[0,1,1]
	v_pk_fma_f32 v[38:39], v[108:109], v[38:39], v[178:179] op_sel_hi:[0,1,1]
	v_pk_fma_f32 v[36:37], v[108:109], v[36:37], v[180:181] op_sel_hi:[0,1,1]
	v_pk_fma_f32 v[34:35], v[108:109], v[34:35], v[182:183] op_sel_hi:[0,1,1]
	v_pk_mul_f32 v[184:185], v[32:33], v[98:99]
	v_pk_mul_f32 v[176:177], v[112:113], v[128:129] op_sel_hi:[1,0]
	v_pk_fma_f32 v[184:185], v[38:39], v[100:101], v[184:185]
	v_pk_mul_f32 v[178:179], v[114:115], v[128:129] op_sel_hi:[1,0]
	v_pk_fma_f32 v[184:185], v[36:37], v[102:103], v[184:185]
	v_pk_mul_f32 v[180:181], v[116:117], v[128:129] op_sel_hi:[1,0]
	v_pk_fma_f32 v[184:185], v[34:35], v[104:105], v[184:185]
	v_pk_mul_f32 v[182:183], v[118:119], v[128:129] op_sel_hi:[1,0]
	v_add_f32_e32 v168, v184, v185
	ds_read_b128 v[112:115], v84 offset:13024
	ds_read_b32 v128, v85 offset:13024
	ds_read_b128 v[116:119], v84 offset:13280
	ds_read_b32 v108, v86 offset:12992
	ds_read_b128 v[98:101], v84 offset:12352
	ds_read_b128 v[102:105], v84 offset:12608
	s_waitcnt lgkmcnt(6)
; __device__ __forceinline__ void ssd_scan_unit(CP p, int l, int u, char* smem) {
;     ...
; #pragma unroll 2
;     for (int s = 0; s < 16; ++s) {
;       const float* sb = cb + (s + 1) * SST;
;       const float4 B0n = *reinterpret_cast<const float4*>(sb + j * 4), B1n = *reinterpret_cast<const float4*>(sb + 64 + j * 4);
;       const float4 C0n = *reinterpret_cast<const float4*>(sb + 128 + j * 4), C1n = *reinterpret_cast<const float4*>(sb + 192 + j * 4);
;       const float xdtn = sb[256 + prow], xrn = sb[272 + prow], an = sb[288];
;       __builtin_amdgcn_sched_barrier(0);
;       hs[0] = fmaf(a, hs[0], xdt * B0.x); hs[1] = fmaf(a, hs[1], xdt * B0.y); hs[2] = fmaf(a, hs[2], xdt * B0.z); hs[3] = fmaf(a, hs[3], xdt * B0.w);
;       hs[4] = fmaf(a, hs[4], xdt * B1.x); hs[5] = fmaf(a, hs[5], xdt * B1.y); hs[6] = fmaf(a, hs[6], xdt * B1.z); hs[7] = fmaf(a, hs[7], xdt * B1.w);
;       float y = hs[0] * C0.x + hs[1] * C0.y + hs[2] * C0.z + hs[3] * C0.w + hs[4] * C1.x + hs[5] * C1.y + hs[6] * C1.z + hs[7] * C1.w;
;       y = allreduce16(y);
;       y = fmaf(Dh, xr, y);
;       if (j == s) ykeep = y;
;       B0 = B0n; B1 = B1n; C0 = C0n; C1 = C1n; xdt = xdtn; xr = xrn; a = an;
;     }
	v_pk_fma_f32 v[32:33], v[130:131], v[32:33], v[176:177] op_sel_hi:[0,1,1]
	v_pk_fma_f32 v[38:39], v[130:131], v[38:39], v[178:179] op_sel_hi:[0,1,1]
	v_pk_fma_f32 v[36:37], v[130:131], v[36:37], v[180:181] op_sel_hi:[0,1,1]
	v_pk_fma_f32 v[34:35], v[130:131], v[34:35], v[182:183] op_sel_hi:[0,1,1]
	v_pk_mul_f32 v[184:185], v[32:33], v[120:121]
	v_pk_mul_f32 v[176:177], v[90:91], v[106:107] op_sel_hi:[1,0]
	v_pk_fma_f32 v[184:185], v[38:39], v[122:123], v[184:185]
	v_pk_mul_f32 v[178:179], v[92:93], v[106:107] op_sel_hi:[1,0]
	v_pk_fma_f32 v[184:185], v[36:37], v[124:125], v[184:185]
	v_pk_mul_f32 v[180:181], v[94:95], v[106:107] op_sel_hi:[1,0]
	v_pk_fma_f32 v[184:185], v[34:35], v[126:127], v[184:185]
	v_pk_mul_f32 v[182:183], v[96:97], v[106:107] op_sel_hi:[1,0]
	v_add_f32_e32 v169, v184, v185
	ds_read_b128 v[90:93], v84 offset:14208
	ds_read_b32 v106, v85 offset:14208
	ds_read_b128 v[94:97], v84 offset:14464
	ds_read_b32 v130, v86 offset:14176
	ds_read_b128 v[120:123], v84 offset:13536
	ds_read_b128 v[124:127], v84 offset:13792
	s_waitcnt lgkmcnt(6)
	v_pk_fma_f32 v[32:33], v[108:109], v[32:33], v[176:177] op_sel_hi:[0,1,1]
	v_pk_fma_f32 v[38:39], v[108:109], v[38:39], v[178:179] op_sel_hi:[0,1,1]
	v_pk_fma_f32 v[36:37], v[108:109], v[36:37], v[180:181] op_sel_hi:[0,1,1]
	v_pk_fma_f32 v[34:35], v[108:109], v[34:35], v[182:183] op_sel_hi:[0,1,1]
	v_pk_mul_f32 v[184:185], v[32:33], v[98:99]
	v_pk_mul_f32 v[176:177], v[112:113], v[128:129] op_sel_hi:[1,0]
	v_pk_fma_f32 v[184:185], v[38:39], v[100:101], v[184:185]
	v_pk_mul_f32 v[178:179], v[114:115], v[128:129] op_sel_hi:[1,0]
	v_pk_fma_f32 v[184:185], v[36:37], v[102:103], v[184:185]
	v_pk_mul_f32 v[180:181], v[116:117], v[128:129] op_sel_hi:[1,0]
	v_pk_fma_f32 v[184:185], v[34:35], v[104:105], v[184:185]
	v_pk_mul_f32 v[182:183], v[118:119], v[128:129] op_sel_hi:[1,0]
	v_add_f32_e32 v170, v184, v185
	ds_read_b128 v[112:115], v84 offset:15392
	ds_read_b32 v128, v85 offset:15392
	ds_read_b128 v[116:119], v84 offset:15648
	ds_read_b32 v108, v86 offset:15360
	ds_read_b128 v[98:101], v84 offset:14720
	ds_read_b128 v[102:105], v84 offset:14976
	s_waitcnt lgkmcnt(6)
	v_pk_fma_f32 v[32:33], v[130:131], v[32:33], v[176:177] op_sel_hi:[0,1,1]
	v_pk_fma_f32 v[38:39], v[130:131], v[38:39], v[178:179] op_sel_hi:[0,1,1]
	v_pk_fma_f32 v[36:37], v[130:131], v[36:37], v[180:181] op_sel_hi:[0,1,1]
	v_pk_fma_f32 v[34:35], v[130:131], v[34:35], v[182:183] op_sel_hi:[0,1,1]
	v_pk_mul_f32 v[184:185], v[32:33], v[120:121]
	v_pk_mul_f32 v[176:177], v[90:91], v[106:107] op_sel_hi:[1,0]
	v_pk_fma_f32 v[184:185], v[38:39], v[122:123], v[184:185]
	v_pk_mul_f32 v[178:179], v[92:93], v[106:107] op_sel_hi:[1,0]
	v_pk_fma_f32 v[184:185], v[36:37], v[124:125], v[184:185]
	v_pk_mul_f32 v[180:181], v[94:95], v[106:107] op_sel_hi:[1,0]
	v_pk_fma_f32 v[184:185], v[34:35], v[126:127], v[184:185]
	v_pk_mul_f32 v[182:183], v[96:97], v[106:107] op_sel_hi:[1,0]
	v_add_f32_e32 v171, v184, v185
	ds_read_b128 v[90:93], v84 offset:16576
	ds_read_b32 v106, v85 offset:16576
	ds_read_b128 v[94:97], v84 offset:16832
	ds_read_b32 v130, v86 offset:16544
	ds_read_b128 v[120:123], v84 offset:15904
	ds_read_b128 v[124:127], v84 offset:16160
	s_waitcnt lgkmcnt(6)
	v_pk_fma_f32 v[32:33], v[108:109], v[32:33], v[176:177] op_sel_hi:[0,1,1]
	v_pk_fma_f32 v[38:39], v[108:109], v[38:39], v[178:179] op_sel_hi:[0,1,1]
	v_pk_fma_f32 v[36:37], v[108:109], v[36:37], v[180:181] op_sel_hi:[0,1,1]
	v_pk_fma_f32 v[34:35], v[108:109], v[34:35], v[182:183] op_sel_hi:[0,1,1]
	v_pk_mul_f32 v[184:185], v[32:33], v[98:99]
	v_pk_mul_f32 v[176:177], v[112:113], v[128:129] op_sel_hi:[1,0]
	v_pk_fma_f32 v[184:185], v[38:39], v[100:101], v[184:185]
	v_pk_mul_f32 v[178:179], v[114:115], v[128:129] op_sel_hi:[1,0]
	v_pk_fma_f32 v[184:185], v[36:37], v[102:103], v[184:185]
	v_pk_mul_f32 v[180:181], v[116:117], v[128:129] op_sel_hi:[1,0]
	v_pk_fma_f32 v[184:185], v[34:35], v[104:105], v[184:185]
	v_pk_mul_f32 v[182:183], v[118:119], v[128:129] op_sel_hi:[1,0]
	v_add_f32_e32 v172, v184, v185
	ds_read_b128 v[112:115], v84 offset:17760
	ds_read_b32 v128, v85 offset:17760
	ds_read_b128 v[116:119], v84 offset:18016
	ds_read_b32 v108, v86 offset:17728
	ds_read_b128 v[98:101], v84 offset:17088
	ds_read_b128 v[102:105], v84 offset:17344
	s_waitcnt lgkmcnt(6)
	v_pk_fma_f32 v[32:33], v[130:131], v[32:33], v[176:177] op_sel_hi:[0,1,1]
	v_pk_fma_f32 v[38:39], v[130:131], v[38:39], v[178:179] op_sel_hi:[0,1,1]
	v_pk_fma_f32 v[36:37], v[130:131], v[36:37], v[180:181] op_sel_hi:[0,1,1]
	v_pk_fma_f32 v[34:35], v[130:131], v[34:35], v[182:183] op_sel_hi:[0,1,1]
	v_pk_mul_f32 v[184:185], v[32:33], v[120:121]
	v_pk_mul_f32 v[176:177], v[90:91], v[106:107] op_sel_hi:[1,0]
	v_pk_fma_f32 v[184:185], v[38:39], v[122:123], v[184:185]
	v_pk_mul_f32 v[178:179], v[92:93], v[106:107] op_sel_hi:[1,0]
	v_pk_fma_f32 v[184:185], v[36:37], v[124:125], v[184:185]
	v_pk_mul_f32 v[180:181], v[94:95], v[106:107] op_sel_hi:[1,0]
	v_pk_fma_f32 v[184:185], v[34:35], v[126:127], v[184:185]
	v_pk_mul_f32 v[182:183], v[96:97], v[106:107] op_sel_hi:[1,0]
	v_add_f32_e32 v173, v184, v185
	ds_read_b32 v130, v86 offset:18912
	ds_read_b128 v[120:123], v84 offset:18272
	ds_read_b128 v[124:127], v84 offset:18528
	s_waitcnt lgkmcnt(3)
; __device__ __forceinline__ float bf2f(bf16_t v) { return __uint_as_float(((unsigned)v) << 16); }
; __device__ __forceinline__ bf16_t f2bf(float f) { return (bf16_t)(pack2(f, 0.f) & 0xffffu); }
; __device__ __forceinline__ float lo2f(unsigned w) { return __uint_as_float(w << 16); }
; __device__ __forceinline__ float hi2f(unsigned w) { return __uint_as_float(w & 0xffff0000u); }
; __device__ __forceinline__ void ssd_scan_unit(CP p, int l, int u, char* smem) {
;     ...
;   auto lwrite = [&](int bi) {
; #pragma unroll
;     for (int x = 0; x < 2; ++x) {
;       const int e = tid + x * 256, tok = e >> 5, rem = e & 31, which = rem >> 4, part = rem & 15;
;       float* d = buf + bi * 16 * SST + tok * SST + which * 128 + part * 8;
;       *reinterpret_cast<float4*>(d) = make_float4(lo2f(st[x].x), hi2f(st[x].x), lo2f(st[x].y), hi2f(st[x].y));
;       *reinterpret_cast<float4*>(d + 4) = make_float4(lo2f(st[x].z), hi2f(st[x].z), lo2f(st[x].w), hi2f(st[x].w));
;     }
;     {
;       const int tok = tid >> 4, pp = tid & 15;
;       float* d = buf + bi * 16 * SST + tok * SST;
;       const float stx = bf2f(stxr);
;       d[256 + pp] = stx * stdt;
;       d[272 + pp] = stx;
;       if (pp == 0) d[288] = __expf(stdt * Ah);
;     }
;   };
;     ...
;       hs[0] = fmaf(a, hs[0], xdt * B0.x); hs[1] = fmaf(a, hs[1], xdt * B0.y); hs[2] = fmaf(a, hs[2], xdt * B0.z); hs[3] = fmaf(a, hs[3], xdt * B0.w);
;       hs[4] = fmaf(a, hs[4], xdt * B1.x); hs[5] = fmaf(a, hs[5], xdt * B1.y); hs[6] = fmaf(a, hs[6], xdt * B1.z); hs[7] = fmaf(a, hs[7], xdt * B1.w);
;       float y = hs[0] * C0.x + hs[1] * C0.y + hs[2] * C0.z + hs[3] * C0.w + hs[4] * C1.x + hs[5] * C1.y + hs[6] * C1.z + hs[7] * C1.w;
;       y = allreduce16(y);
;       y = fmaf(Dh, xr, y);
;       if (j == s) ykeep = y;
;       B0 = B0n; B1 = B1n; C0 = C0n; C1 = C1n; xdt = xdtn; xr = xrn; a = an;
;     }
;     Y[(size_t)(rowof(b, c * 16) + j) * 1024 + h * 64 + q * 16 + prow] = f2bf(ykeep);
;     if (c + 1 < NCH) lwrite((c + 1) & 1);
;     half_barrier(smem);
	v_pk_fma_f32 v[32:33], v[108:109], v[32:33], v[176:177] op_sel_hi:[0,1,1]
	v_pk_fma_f32 v[38:39], v[108:109], v[38:39], v[178:179] op_sel_hi:[0,1,1]
	v_pk_fma_f32 v[36:37], v[108:109], v[36:37], v[180:181] op_sel_hi:[0,1,1]
	v_pk_fma_f32 v[34:35], v[108:109], v[34:35], v[182:183] op_sel_hi:[0,1,1]
	v_pk_mul_f32 v[184:185], v[32:33], v[98:99]
	v_pk_mul_f32 v[176:177], v[112:113], v[128:129] op_sel_hi:[1,0]
	v_pk_fma_f32 v[184:185], v[38:39], v[100:101], v[184:185]
	v_pk_mul_f32 v[178:179], v[114:115], v[128:129] op_sel_hi:[1,0]
	v_pk_fma_f32 v[184:185], v[36:37], v[102:103], v[184:185]
	v_pk_mul_f32 v[180:181], v[116:117], v[128:129] op_sel_hi:[1,0]
	v_pk_fma_f32 v[184:185], v[34:35], v[104:105], v[184:185]
	v_pk_mul_f32 v[182:183], v[118:119], v[128:129] op_sel_hi:[1,0]
	v_add_f32_e32 v174, v184, v185
	s_waitcnt lgkmcnt(0)
	v_pk_fma_f32 v[32:33], v[130:131], v[32:33], v[176:177] op_sel_hi:[0,1,1]
	v_pk_fma_f32 v[38:39], v[130:131], v[38:39], v[178:179] op_sel_hi:[0,1,1]
	v_pk_fma_f32 v[36:37], v[130:131], v[36:37], v[180:181] op_sel_hi:[0,1,1]
	v_pk_fma_f32 v[34:35], v[130:131], v[34:35], v[182:183] op_sel_hi:[0,1,1]
	v_pk_mul_f32 v[184:185], v[32:33], v[120:121]
	v_pk_fma_f32 v[184:185], v[38:39], v[122:123], v[184:185]
	v_pk_fma_f32 v[184:185], v[36:37], v[124:125], v[184:185]
	v_pk_fma_f32 v[184:185], v[34:35], v[126:127], v[184:185]
	v_add_f32_e32 v175, v184, v185
	v_add_f32_dpp v160, v160, v160 row_ror:8 row_mask:0xf bank_mask:0x3 bound_ctrl:1
	v_add_f32_dpp v161, v161, v161 row_ror:8 row_mask:0xf bank_mask:0x3 bound_ctrl:1
	v_add_f32_dpp v162, v162, v162 row_ror:8 row_mask:0xf bank_mask:0x3 bound_ctrl:1
	v_add_f32_dpp v163, v163, v163 row_ror:8 row_mask:0xf bank_mask:0x3 bound_ctrl:1
	v_add_f32_dpp v164, v164, v164 row_ror:8 row_mask:0xf bank_mask:0x3 bound_ctrl:1
	v_add_f32_dpp v165, v165, v165 row_ror:8 row_mask:0xf bank_mask:0x3 bound_ctrl:1
	v_add_f32_dpp v166, v166, v166 row_ror:8 row_mask:0xf bank_mask:0x3 bound_ctrl:1
	v_add_f32_dpp v167, v167, v167 row_ror:8 row_mask:0xf bank_mask:0x3 bound_ctrl:1
	v_add_f32_dpp v160, v168, v168 row_ror:8 row_mask:0xf bank_mask:0xc bound_ctrl:1
	v_add_f32_dpp v161, v169, v169 row_ror:8 row_mask:0xf bank_mask:0xc bound_ctrl:1
	v_add_f32_dpp v162, v170, v170 row_ror:8 row_mask:0xf bank_mask:0xc bound_ctrl:1
	v_add_f32_dpp v163, v171, v171 row_ror:8 row_mask:0xf bank_mask:0xc bound_ctrl:1
	v_add_f32_dpp v164, v172, v172 row_ror:8 row_mask:0xf bank_mask:0xc bound_ctrl:1
	v_add_f32_dpp v165, v173, v173 row_ror:8 row_mask:0xf bank_mask:0xc bound_ctrl:1
	v_add_f32_dpp v166, v174, v174 row_ror:8 row_mask:0xf bank_mask:0xc bound_ctrl:1
	v_add_f32_dpp v167, v175, v175 row_ror:8 row_mask:0xf bank_mask:0xc bound_ctrl:1
	v_add_f32_dpp v160, v160, v160 row_half_mirror row_mask:0xf bank_mask:0x5 bound_ctrl:1
	v_add_f32_dpp v161, v161, v161 row_half_mirror row_mask:0xf bank_mask:0x5 bound_ctrl:1
	v_add_f32_dpp v162, v162, v162 row_half_mirror row_mask:0xf bank_mask:0x5 bound_ctrl:1
	v_add_f32_dpp v163, v163, v163 row_half_mirror row_mask:0xf bank_mask:0x5 bound_ctrl:1
	v_add_f32_dpp v160, v164, v164 row_half_mirror row_mask:0xf bank_mask:0xa bound_ctrl:1
	v_add_f32_dpp v161, v165, v165 row_half_mirror row_mask:0xf bank_mask:0xa bound_ctrl:1
	v_add_f32_dpp v162, v166, v166 row_half_mirror row_mask:0xf bank_mask:0xa bound_ctrl:1
	v_add_f32_dpp v163, v167, v167 row_half_mirror row_mask:0xf bank_mask:0xa bound_ctrl:1
	v_and_b32_e32 v188, 2, v44
	v_cmp_ne_u32_e32 vcc, 0, v188
	v_and_b32_e32 v188, 1, v44
	s_nop 0
	v_cndmask_b32_e32 v189, v160, v162, vcc
	v_cndmask_b32_e32 v190, v162, v160, vcc
	v_cndmask_b32_e32 v191, v161, v163, vcc
	v_cndmask_b32_e32 v192, v163, v161, vcc
	v_cmp_ne_u32_e32 vcc, 0, v188
	v_add_f32_dpp v160, v190, v189 quad_perm:[2,3,0,1] row_mask:0xf bank_mask:0xf bound_ctrl:1
	v_add_f32_dpp v161, v192, v191 quad_perm:[2,3,0,1] row_mask:0xf bank_mask:0xf bound_ctrl:1
	v_cndmask_b32_e32 v189, v160, v161, vcc
	v_cndmask_b32_e32 v190, v161, v160, vcc
	s_nop 1
	v_add_f32_dpp v187, v190, v189 quad_perm:[1,0,3,2] row_mask:0xf bank_mask:0xf bound_ctrl:1
	v_fma_f32 v60, v43, v186, v187
	s_add_i32 s5, s5, s11
	s_cmp_eq_u32 s4, 0
	s_cselect_b32 s4, s10, s5
	s_waitcnt lgkmcnt(2)
	v_or_b32_e32 v8, s4, v44
	v_ashrrev_i32_e32 v9, 31, v8
	v_lshlrev_b64 v[8:9], 11, v[8:9]
	v_cvt_pk_bf16_f32 v10, v60, s0
	v_lshl_add_u64 v[8:9], v[28:29], 0, v[8:9]
	s_and_b64 vcc, exec, s[2:3]
	global_store_short v[8:9], v10, off
	s_cbranch_vccz .LBB0_552
	s_bitcmp1_b32 s28, 0
	s_cselect_b32 s2, 0x4a00, 0
	s_add_i32 s2, s63, s2
	v_lshl_add_u32 v8, v50, 2, s2
	v_add3_u32 v12, v8, v51, v52
	s_waitcnt vmcnt(4)
	v_lshlrev_b32_e32 v8, 16, v0
	v_and_b32_e32 v9, 0xffff0000, v0
	v_lshlrev_b32_e32 v10, 16, v1
	v_and_b32_e32 v11, 0xffff0000, v1
	ds_write_b128 v12, v[8:11]
	v_lshlrev_b32_e32 v8, 16, v2
	v_and_b32_e32 v9, 0xffff0000, v2
	v_lshlrev_b32_e32 v10, 16, v3
	v_and_b32_e32 v11, 0xffff0000, v3
	ds_write_b128 v12, v[8:11] offset:16
	v_lshl_add_u32 v8, v53, 2, s2
	v_add3_u32 v12, v8, v51, v52
	s_waitcnt vmcnt(3)
	v_lshlrev_b32_e32 v8, 16, v4
	v_and_b32_e32 v9, 0xffff0000, v4
	v_lshlrev_b32_e32 v10, 16, v5
	v_and_b32_e32 v11, 0xffff0000, v5
	ds_write_b128 v12, v[8:11]
	v_lshlrev_b32_e32 v8, 16, v6
	v_and_b32_e32 v9, 0xffff0000, v6
	v_lshlrev_b32_e32 v10, 16, v7
	v_and_b32_e32 v11, 0xffff0000, v7
	ds_write_b128 v12, v[8:11] offset:16
	v_lshl_add_u32 v8, v55, 2, s2
	s_waitcnt vmcnt(2)
	v_lshlrev_b32_e32 v9, 16, v49
	v_lshl_add_u32 v11, v44, 2, v8
	s_waitcnt vmcnt(1)
	v_mul_f32_e32 v10, v54, v9
	v_add_u32_e32 v11, 0x400, v11
	ds_write2_b32 v11, v10, v9 offset1:16
	s_and_saveexec_b64 s[2:3], s[38:39]
	s_cbranch_execz .LBB0_551
	v_mul_f32_e32 v9, v54, v46
	v_mul_f32_e32 v9, 0xbfb8aa3b, v9
	v_exp_f32_e32 v9, v9
	ds_write_b32 v8, v9 offset:1152

; __device__ __forceinline__ void rwkv_scan_unit(CP p, int u, char* smem) {
;     ...
;   for (int c = 0; c < NCH; ++c) {
;     if (c + 1 < NCH) gload(c + 1);
;     const float* cb = buf + (c & 1) * 6144;
;     float ykeep = 0.f;
;     float4 om = *reinterpret_cast<const float4*>(cb + j * 4);
;     float4 kk = *reinterpret_cast<const float4*>(cb + 64 + j * 4);
;     float4 bb = *reinterpret_cast<const float4*>(cb + 128 + j * 4);
;     float4 kp = *reinterpret_cast<const float4*>(cb + 192 + j * 4);
;     float4 rr = *reinterpret_cast<const float4*>(cb + 256 + j * 4);
;     float vv = cb[320 + rowv];
; #pragma unroll 2
;     for (int s = 0; s < 16; ++s) {
;       const float* sb = cb + (s + 1) * 384;
;       const float4 om_n = *reinterpret_cast<const float4*>(sb + j * 4);
;       const float4 kk_n = *reinterpret_cast<const float4*>(sb + 64 + j * 4);
;       const float4 bb_n = *reinterpret_cast<const float4*>(sb + 128 + j * 4);
;       const float4 kp_n = *reinterpret_cast<const float4*>(sb + 192 + j * 4);
;       const float4 rr_n = *reinterpret_cast<const float4*>(sb + 256 + j * 4);
;       const float vv_n = sb[320 + rowv];
;       __builtin_amdgcn_sched_barrier(0);
;       float d = s0 * kk.x + s1 * kk.y + s2 * kk.z + s3 * kk.w;
;       d = allreduce16(d);
;       const float sa = -d;
;       s0 = fmaf(-s0, om.x, s0); s1 = fmaf(-s1, om.y, s1); s2 = fmaf(-s2, om.z, s2); s3 = fmaf(-s3, om.w, s3);
;       s0 = fmaf(sa, bb.x, s0); s1 = fmaf(sa, bb.y, s1); s2 = fmaf(sa, bb.z, s2); s3 = fmaf(sa, bb.w, s3);
;       s0 = fmaf(vv, kp.x, s0); s1 = fmaf(vv, kp.y, s1); s2 = fmaf(vv, kp.z, s2); s3 = fmaf(vv, kp.w, s3);
;       float y = s0 * rr.x + s1 * rr.y + s2 * rr.z + s3 * rr.w;
;       y = allreduce16(y);
;       if (j == s) ykeep = y;
;       om = om_n; kk = kk_n; bb = bb_n; kp = kp_n; rr = rr_n; vv = vv_n;
;     }
.Lrw_head:
	s_add_i32 s28, s4, 1
	s_bitcmp1_b32 s4, 0
	s_cselect_b32 s12, 0x6000, 0
	s_add_i32 s13, s63, s12
	v_lshl_add_u32 v78, v77, 2, s13
	v_lshl_add_u32 v79, v48, 2, s13
	ds_read_b128 v[94:97], v78 offset:256
	ds_read_b128 v[90:93], v78 offset:0
	ds_read_b128 v[102:105], v78 offset:768
	ds_read_b32 v110, v79 offset:1280
	ds_read_b128 v[98:101], v78 offset:512
	ds_read_b128 v[106:109], v78 offset:1024
	ds_read_b128 v[116:119], v78 offset:1792
	ds_read_b128 v[112:115], v78 offset:1536
	ds_read_b128 v[124:127], v78 offset:2304
	ds_read_b32 v132, v79 offset:2816
	ds_read_b128 v[120:123], v78 offset:2048
	ds_read_b128 v[128:131], v78 offset:2560
	s_waitcnt lgkmcnt(7)
	v_pk_mul_f32 v[176:177], v[60:61], v[94:95]
	v_pk_fma_f32 v[176:177], v[58:59], v[96:97], v[176:177]
	ds_read_b128 v[138:141], v78 offset:3328
	ds_read_b128 v[134:137], v78 offset:3072
	v_pk_fma_f32 v[180:181], v[60:61], v[90:91], v[60:61] neg_lo:[1,0,0] neg_hi:[1,0,0]
	v_add_f32_e32 v178, v176, v177
	v_pk_fma_f32 v[182:183], v[58:59], v[92:93], v[58:59] neg_lo:[1,0,0] neg_hi:[1,0,0]
	ds_read_b128 v[152:155], v78 offset:3840
	v_add_f32_dpp v178, v178, v178 quad_perm:[1,0,3,2] row_mask:0xf bank_mask:0xf bound_ctrl:1
	v_pk_fma_f32 v[180:181], v[110:111], v[102:103], v[180:181] op_sel_hi:[0,1,1]
	v_pk_fma_f32 v[182:183], v[110:111], v[104:105], v[182:183] op_sel_hi:[0,1,1]
	v_add_f32_dpp v178, v178, v178 quad_perm:[2,3,0,1] row_mask:0xf bank_mask:0xf bound_ctrl:1
	ds_read_b32 v146, v79 offset:4352
	ds_read_b128 v[142:145], v78 offset:3584
	v_add_f32_dpp v178, v178, v178 row_half_mirror row_mask:0xf bank_mask:0xf bound_ctrl:1
	ds_read_b128 v[156:159], v78 offset:4096
	s_nop 0
	v_add_f32_dpp v178, v178, v178 row_mirror row_mask:0xf bank_mask:0xf bound_ctrl:1
	v_pk_fma_f32 v[60:61], v[178:179], v[98:99], v[180:181] op_sel_hi:[0,1,1] neg_lo:[1,0,0] neg_hi:[1,0,0]
	v_pk_fma_f32 v[58:59], v[178:179], v[100:101], v[182:183] op_sel_hi:[0,1,1] neg_lo:[1,0,0] neg_hi:[1,0,0]
	s_waitcnt lgkmcnt(7)
	v_pk_mul_f32 v[176:177], v[60:61], v[116:117]
	v_pk_fma_f32 v[176:177], v[58:59], v[118:119], v[176:177]
	ds_read_b128 v[94:97], v78 offset:4864
	ds_read_b128 v[90:93], v78 offset:4608
	v_pk_fma_f32 v[180:181], v[60:61], v[112:113], v[60:61] neg_lo:[1,0,0] neg_hi:[1,0,0]
	v_add_f32_e32 v178, v176, v177
	v_pk_fma_f32 v[182:183], v[58:59], v[114:115], v[58:59] neg_lo:[1,0,0] neg_hi:[1,0,0]
	ds_read_b128 v[102:105], v78 offset:5376
	v_add_f32_dpp v178, v178, v178 quad_perm:[1,0,3,2] row_mask:0xf bank_mask:0xf bound_ctrl:1
	v_pk_fma_f32 v[180:181], v[132:133], v[124:125], v[180:181] op_sel_hi:[0,1,1]
	v_pk_fma_f32 v[182:183], v[132:133], v[126:127], v[182:183] op_sel_hi:[0,1,1]
	v_add_f32_dpp v178, v178, v178 quad_perm:[2,3,0,1] row_mask:0xf bank_mask:0xf bound_ctrl:1
	v_pk_mul_f32 v[184:185], v[60:61], v[106:107]
	v_pk_fma_f32 v[184:185], v[58:59], v[108:109], v[184:185]
	v_add_f32_dpp v178, v178, v178 row_half_mirror row_mask:0xf bank_mask:0xf bound_ctrl:1
	v_add_f32_e32 v160, v184, v185
	ds_read_b32 v110, v79 offset:5888
	v_add_f32_dpp v178, v178, v178 row_mirror row_mask:0xf bank_mask:0xf bound_ctrl:1
	ds_read_b128 v[98:101], v78 offset:5120
	ds_read_b128 v[106:109], v78 offset:5632
	v_pk_fma_f32 v[60:61], v[178:179], v[120:121], v[180:181] op_sel_hi:[0,1,1] neg_lo:[1,0,0] neg_hi:[1,0,0]
	v_pk_fma_f32 v[58:59], v[178:179], v[122:123], v[182:183] op_sel_hi:[0,1,1] neg_lo:[1,0,0] neg_hi:[1,0,0]
	s_waitcnt lgkmcnt(7)
	v_pk_mul_f32 v[176:177], v[60:61], v[138:139]
	v_pk_fma_f32 v[176:177], v[58:59], v[140:141], v[176:177]
	ds_read_b128 v[116:119], v78 offset:6400
	ds_read_b128 v[112:115], v78 offset:6144
	v_pk_fma_f32 v[180:181], v[60:61], v[134:135], v[60:61] neg_lo:[1,0,0] neg_hi:[1,0,0]
	v_add_f32_e32 v178, v176, v177
	v_pk_fma_f32 v[182:183], v[58:59], v[136:137], v[58:59] neg_lo:[1,0,0] neg_hi:[1,0,0]
	ds_read_b128 v[124:127], v78 offset:6912
	v_add_f32_dpp v178, v178, v178 quad_perm:[1,0,3,2] row_mask:0xf bank_mask:0xf bound_ctrl:1
	v_pk_fma_f32 v[180:181], v[146:147], v[152:153], v[180:181] op_sel_hi:[0,1,1]
	v_pk_fma_f32 v[182:183], v[146:147], v[154:155], v[182:183] op_sel_hi:[0,1,1]
	v_add_f32_dpp v178, v178, v178 quad_perm:[2,3,0,1] row_mask:0xf bank_mask:0xf bound_ctrl:1
	v_pk_mul_f32 v[184:185], v[60:61], v[128:129]
	v_pk_fma_f32 v[184:185], v[58:59], v[130:131], v[184:185]
	v_add_f32_dpp v178, v178, v178 row_half_mirror row_mask:0xf bank_mask:0xf bound_ctrl:1
	v_add_f32_e32 v161, v184, v185
	ds_read_b32 v132, v79 offset:7424
	v_add_f32_dpp v178, v178, v178 row_mirror row_mask:0xf bank_mask:0xf bound_ctrl:1
	ds_read_b128 v[120:123], v78 offset:6656
	ds_read_b128 v[128:131], v78 offset:7168
	v_pk_fma_f32 v[60:61], v[178:179], v[142:143], v[180:181] op_sel_hi:[0,1,1] neg_lo:[1,0,0] neg_hi:[1,0,0]
	v_pk_fma_f32 v[58:59], v[178:179], v[144:145], v[182:183] op_sel_hi:[0,1,1] neg_lo:[1,0,0] neg_hi:[1,0,0]
	s_waitcnt lgkmcnt(7)
	v_pk_mul_f32 v[176:177], v[60:61], v[94:95]
	v_pk_fma_f32 v[176:177], v[58:59], v[96:97], v[176:177]
	ds_read_b128 v[138:141], v78 offset:7936
	ds_read_b128 v[134:137], v78 offset:7680
	v_pk_fma_f32 v[180:181], v[60:61], v[90:91], v[60:61] neg_lo:[1,0,0] neg_hi:[1,0,0]
	v_add_f32_e32 v178, v176, v177
	v_pk_fma_f32 v[182:183], v[58:59], v[92:93], v[58:59] neg_lo:[1,0,0] neg_hi:[1,0,0]
	ds_read_b128 v[152:155], v78 offset:8448
	v_add_f32_dpp v178, v178, v178 quad_perm:[1,0,3,2] row_mask:0xf bank_mask:0xf bound_ctrl:1
	v_pk_fma_f32 v[180:181], v[110:111], v[102:103], v[180:181] op_sel_hi:[0,1,1]
	v_pk_fma_f32 v[182:183], v[110:111], v[104:105], v[182:183] op_sel_hi:[0,1,1]
	v_add_f32_dpp v178, v178, v178 quad_perm:[2,3,0,1] row_mask:0xf bank_mask:0xf bound_ctrl:1
	v_pk_mul_f32 v[184:185], v[60:61], v[156:157]
	v_pk_fma_f32 v[184:185], v[58:59], v[158:159], v[184:185]
	v_add_f32_dpp v178, v178, v178 row_half_mirror row_mask:0xf bank_mask:0xf bound_ctrl:1
	v_add_f32_e32 v162, v184, v185
	ds_read_b32 v146, v79 offset:8960
	v_add_f32_dpp v178, v178, v178 row_mirror row_mask:0xf bank_mask:0xf bound_ctrl:1
	ds_read_b128 v[142:145], v78 offset:8192
	ds_read_b128 v[156:159], v78 offset:8704
	v_pk_fma_f32 v[60:61], v[178:179], v[98:99], v[180:181] op_sel_hi:[0,1,1] neg_lo:[1,0,0] neg_hi:[1,0,0]
	v_pk_fma_f32 v[58:59], v[178:179], v[100:101], v[182:183] op_sel_hi:[0,1,1] neg_lo:[1,0,0] neg_hi:[1,0,0]
	s_waitcnt lgkmcnt(7)
; __device__ __forceinline__ void rwkv_scan_unit(CP p, int u, char* smem) {
;     ...
;     for (int s = 0; s < 16; ++s) {
;       const float* sb = cb + (s + 1) * 384;
;       const float4 om_n = *reinterpret_cast<const float4*>(sb + j * 4);
;       const float4 kk_n = *reinterpret_cast<const float4*>(sb + 64 + j * 4);
;       const float4 bb_n = *reinterpret_cast<const float4*>(sb + 128 + j * 4);
;       const float4 kp_n = *reinterpret_cast<const float4*>(sb + 192 + j * 4);
;       const float4 rr_n = *reinterpret_cast<const float4*>(sb + 256 + j * 4);
;       const float vv_n = sb[320 + rowv];
;       __builtin_amdgcn_sched_barrier(0);
;       float d = s0 * kk.x + s1 * kk.y + s2 * kk.z + s3 * kk.w;
;       d = allreduce16(d);
;       const float sa = -d;
;       s0 = fmaf(-s0, om.x, s0); s1 = fmaf(-s1, om.y, s1); s2 = fmaf(-s2, om.z, s2); s3 = fmaf(-s3, om.w, s3);
;       s0 = fmaf(sa, bb.x, s0); s1 = fmaf(sa, bb.y, s1); s2 = fmaf(sa, bb.z, s2); s3 = fmaf(sa, bb.w, s3);
;       s0 = fmaf(vv, kp.x, s0); s1 = fmaf(vv, kp.y, s1); s2 = fmaf(vv, kp.z, s2); s3 = fmaf(vv, kp.w, s3);
;       float y = s0 * rr.x + s1 * rr.y + s2 * rr.z + s3 * rr.w;
;       y = allreduce16(y);
;       if (j == s) ykeep = y;
;       om = om_n; kk = kk_n; bb = bb_n; kp = kp_n; rr = rr_n; vv = vv_n;
;     }
	v_pk_mul_f32 v[176:177], v[60:61], v[116:117]
	v_pk_fma_f32 v[176:177], v[58:59], v[118:119], v[176:177]
	ds_read_b128 v[94:97], v78 offset:9472
	ds_read_b128 v[90:93], v78 offset:9216
	v_pk_fma_f32 v[180:181], v[60:61], v[112:113], v[60:61] neg_lo:[1,0,0] neg_hi:[1,0,0]
	v_add_f32_e32 v178, v176, v177
	v_pk_fma_f32 v[182:183], v[58:59], v[114:115], v[58:59] neg_lo:[1,0,0] neg_hi:[1,0,0]
	ds_read_b128 v[102:105], v78 offset:9984
	v_add_f32_dpp v178, v178, v178 quad_perm:[1,0,3,2] row_mask:0xf bank_mask:0xf bound_ctrl:1
	v_pk_fma_f32 v[180:181], v[132:133], v[124:125], v[180:181] op_sel_hi:[0,1,1]
	v_pk_fma_f32 v[182:183], v[132:133], v[126:127], v[182:183] op_sel_hi:[0,1,1]
	v_add_f32_dpp v178, v178, v178 quad_perm:[2,3,0,1] row_mask:0xf bank_mask:0xf bound_ctrl:1
	v_pk_mul_f32 v[184:185], v[60:61], v[106:107]
	v_pk_fma_f32 v[184:185], v[58:59], v[108:109], v[184:185]
	v_add_f32_dpp v178, v178, v178 row_half_mirror row_mask:0xf bank_mask:0xf bound_ctrl:1
	v_add_f32_e32 v163, v184, v185
	ds_read_b32 v110, v79 offset:10496
	v_add_f32_dpp v178, v178, v178 row_mirror row_mask:0xf bank_mask:0xf bound_ctrl:1
	ds_read_b128 v[98:101], v78 offset:9728
	ds_read_b128 v[106:109], v78 offset:10240
	v_pk_fma_f32 v[60:61], v[178:179], v[120:121], v[180:181] op_sel_hi:[0,1,1] neg_lo:[1,0,0] neg_hi:[1,0,0]
	v_pk_fma_f32 v[58:59], v[178:179], v[122:123], v[182:183] op_sel_hi:[0,1,1] neg_lo:[1,0,0] neg_hi:[1,0,0]
	s_waitcnt lgkmcnt(7)
	v_pk_mul_f32 v[176:177], v[60:61], v[138:139]
	v_pk_fma_f32 v[176:177], v[58:59], v[140:141], v[176:177]
	ds_read_b128 v[116:119], v78 offset:11008
	ds_read_b128 v[112:115], v78 offset:10752
	v_pk_fma_f32 v[180:181], v[60:61], v[134:135], v[60:61] neg_lo:[1,0,0] neg_hi:[1,0,0]
	v_add_f32_e32 v178, v176, v177
	v_pk_fma_f32 v[182:183], v[58:59], v[136:137], v[58:59] neg_lo:[1,0,0] neg_hi:[1,0,0]
	ds_read_b128 v[124:127], v78 offset:11520
	v_add_f32_dpp v178, v178, v178 quad_perm:[1,0,3,2] row_mask:0xf bank_mask:0xf bound_ctrl:1
	v_pk_fma_f32 v[180:181], v[146:147], v[152:153], v[180:181] op_sel_hi:[0,1,1]
	v_pk_fma_f32 v[182:183], v[146:147], v[154:155], v[182:183] op_sel_hi:[0,1,1]
	v_add_f32_dpp v178, v178, v178 quad_perm:[2,3,0,1] row_mask:0xf bank_mask:0xf bound_ctrl:1
	v_pk_mul_f32 v[184:185], v[60:61], v[128:129]
	v_pk_fma_f32 v[184:185], v[58:59], v[130:131], v[184:185]
	v_add_f32_dpp v178, v178, v178 row_half_mirror row_mask:0xf bank_mask:0xf bound_ctrl:1
	v_add_f32_e32 v164, v184, v185
	ds_read_b32 v132, v79 offset:12032
	v_add_f32_dpp v178, v178, v178 row_mirror row_mask:0xf bank_mask:0xf bound_ctrl:1
	ds_read_b128 v[120:123], v78 offset:11264
	ds_read_b128 v[128:131], v78 offset:11776
	v_pk_fma_f32 v[60:61], v[178:179], v[142:143], v[180:181] op_sel_hi:[0,1,1] neg_lo:[1,0,0] neg_hi:[1,0,0]
	v_pk_fma_f32 v[58:59], v[178:179], v[144:145], v[182:183] op_sel_hi:[0,1,1] neg_lo:[1,0,0] neg_hi:[1,0,0]
	s_waitcnt lgkmcnt(7)
	v_pk_mul_f32 v[176:177], v[60:61], v[94:95]
	v_pk_fma_f32 v[176:177], v[58:59], v[96:97], v[176:177]
	ds_read_b128 v[138:141], v78 offset:12544
	ds_read_b128 v[134:137], v78 offset:12288
	v_pk_fma_f32 v[180:181], v[60:61], v[90:91], v[60:61] neg_lo:[1,0,0] neg_hi:[1,0,0]
	v_add_f32_e32 v178, v176, v177
	v_pk_fma_f32 v[182:183], v[58:59], v[92:93], v[58:59] neg_lo:[1,0,0] neg_hi:[1,0,0]
	ds_read_b128 v[152:155], v78 offset:13056
	v_add_f32_dpp v178, v178, v178 quad_perm:[1,0,3,2] row_mask:0xf bank_mask:0xf bound_ctrl:1
	v_pk_fma_f32 v[180:181], v[110:111], v[102:103], v[180:181] op_sel_hi:[0,1,1]
	v_pk_fma_f32 v[182:183], v[110:111], v[104:105], v[182:183] op_sel_hi:[0,1,1]
	v_add_f32_dpp v178, v178, v178 quad_perm:[2,3,0,1] row_mask:0xf bank_mask:0xf bound_ctrl:1
	v_pk_mul_f32 v[184:185], v[60:61], v[156:157]
	v_pk_fma_f32 v[184:185], v[58:59], v[158:159], v[184:185]
	v_add_f32_dpp v178, v178, v178 row_half_mirror row_mask:0xf bank_mask:0xf bound_ctrl:1
	v_add_f32_e32 v165, v184, v185
	ds_read_b32 v146, v79 offset:13568
	v_add_f32_dpp v178, v178, v178 row_mirror row_mask:0xf bank_mask:0xf bound_ctrl:1
	ds_read_b128 v[142:145], v78 offset:12800
	ds_read_b128 v[156:159], v78 offset:13312
	v_pk_fma_f32 v[60:61], v[178:179], v[98:99], v[180:181] op_sel_hi:[0,1,1] neg_lo:[1,0,0] neg_hi:[1,0,0]
	v_pk_fma_f32 v[58:59], v[178:179], v[100:101], v[182:183] op_sel_hi:[0,1,1] neg_lo:[1,0,0] neg_hi:[1,0,0]
	s_waitcnt lgkmcnt(7)
	v_pk_mul_f32 v[176:177], v[60:61], v[116:117]
	v_pk_fma_f32 v[176:177], v[58:59], v[118:119], v[176:177]
	ds_read_b128 v[94:97], v78 offset:14080
	ds_read_b128 v[90:93], v78 offset:13824
	v_pk_fma_f32 v[180:181], v[60:61], v[112:113], v[60:61] neg_lo:[1,0,0] neg_hi:[1,0,0]
	v_add_f32_e32 v178, v176, v177
	v_pk_fma_f32 v[182:183], v[58:59], v[114:115], v[58:59] neg_lo:[1,0,0] neg_hi:[1,0,0]
	ds_read_b128 v[102:105], v78 offset:14592
	v_add_f32_dpp v178, v178, v178 quad_perm:[1,0,3,2] row_mask:0xf bank_mask:0xf bound_ctrl:1
	v_pk_fma_f32 v[180:181], v[132:133], v[124:125], v[180:181] op_sel_hi:[0,1,1]
	v_pk_fma_f32 v[182:183], v[132:133], v[126:127], v[182:183] op_sel_hi:[0,1,1]
	v_add_f32_dpp v178, v178, v178 quad_perm:[2,3,0,1] row_mask:0xf bank_mask:0xf bound_ctrl:1
	v_pk_mul_f32 v[184:185], v[60:61], v[106:107]
	v_pk_fma_f32 v[184:185], v[58:59], v[108:109], v[184:185]
	v_add_f32_dpp v178, v178, v178 row_half_mirror row_mask:0xf bank_mask:0xf bound_ctrl:1
	v_add_f32_e32 v166, v184, v185
	ds_read_b32 v110, v79 offset:15104
	v_add_f32_dpp v178, v178, v178 row_mirror row_mask:0xf bank_mask:0xf bound_ctrl:1
	ds_read_b128 v[98:101], v78 offset:14336
	ds_read_b128 v[106:109], v78 offset:14848
	v_pk_fma_f32 v[60:61], v[178:179], v[120:121], v[180:181] op_sel_hi:[0,1,1] neg_lo:[1,0,0] neg_hi:[1,0,0]
	v_pk_fma_f32 v[58:59], v[178:179], v[122:123], v[182:183] op_sel_hi:[0,1,1] neg_lo:[1,0,0] neg_hi:[1,0,0]
	s_waitcnt vmcnt(0)
; __device__ __forceinline__ float lo2f(unsigned w) { return __uint_as_float(w << 16); }
; __device__ __forceinline__ float hi2f(unsigned w) { return __uint_as_float(w & 0xffff0000u); }
; __device__ __forceinline__ void rwkv_scan_unit(CP p, int u, char* smem) {
;     ...
;   auto lwrite = [&](int bi) {
; #pragma unroll
;     for (int x = 0; x < 3; ++x) {
;       const int e = tid + x * 256, tok = e / 48, rem = e % 48, vec = rem >> 3, part = rem & 7;
;       float* d = buf + bi * 6144 + tok * 384 + vec * 64 + part * 8;
;       *reinterpret_cast<float4*>(d) = make_float4(lo2f(st[x].x), hi2f(st[x].x), lo2f(st[x].y), hi2f(st[x].y));
;       *reinterpret_cast<float4*>(d + 4) = make_float4(lo2f(st[x].z), hi2f(st[x].z), lo2f(st[x].w), hi2f(st[x].w));
;     }
;     ...
;     for (int s = 0; s < 16; ++s) {
;       const float* sb = cb + (s + 1) * 384;
;       const float4 om_n = *reinterpret_cast<const float4*>(sb + j * 4);
;       const float4 kk_n = *reinterpret_cast<const float4*>(sb + 64 + j * 4);
;       const float4 bb_n = *reinterpret_cast<const float4*>(sb + 128 + j * 4);
;       const float4 kp_n = *reinterpret_cast<const float4*>(sb + 192 + j * 4);
;       const float4 rr_n = *reinterpret_cast<const float4*>(sb + 256 + j * 4);
;       const float vv_n = sb[320 + rowv];
;       __builtin_amdgcn_sched_barrier(0);
;       float d = s0 * kk.x + s1 * kk.y + s2 * kk.z + s3 * kk.w;
;       d = allreduce16(d);
;       const float sa = -d;
;       s0 = fmaf(-s0, om.x, s0); s1 = fmaf(-s1, om.y, s1); s2 = fmaf(-s2, om.z, s2); s3 = fmaf(-s3, om.w, s3);
;       s0 = fmaf(sa, bb.x, s0); s1 = fmaf(sa, bb.y, s1); s2 = fmaf(sa, bb.z, s2); s3 = fmaf(sa, bb.w, s3);
;       s0 = fmaf(vv, kp.x, s0); s1 = fmaf(vv, kp.y, s1); s2 = fmaf(vv, kp.z, s2); s3 = fmaf(vv, kp.w, s3);
;       float y = s0 * rr.x + s1 * rr.y + s2 * rr.z + s3 * rr.w;
;       y = allreduce16(y);
;       if (j == s) ykeep = y;
;       om = om_n; kk = kk_n; bb = bb_n; kp = kp_n; rr = rr_n; vv = vv_n;
;     }
	s_bitcmp1_b32 s28, 0
	s_cselect_b32 s2, 0x6000, 0
	s_add_i32 s2, s63, s2
	v_lshl_add_u32 v12, v67, 2, s2
	v_add3_u32 v18, v12, v68, v69
	v_lshlrev_b32_e32 v12, 16, v0
	v_and_b32_e32 v13, 0xffff0000, v0
	v_lshlrev_b32_e32 v14, 16, v1
	v_and_b32_e32 v15, 0xffff0000, v1
	ds_write_b128 v18, v[12:15]
	v_lshlrev_b32_e32 v12, 16, v2
	v_and_b32_e32 v13, 0xffff0000, v2
	v_lshlrev_b32_e32 v14, 16, v3
	v_and_b32_e32 v15, 0xffff0000, v3
	ds_write_b128 v18, v[12:15] offset:16
	v_lshl_add_u32 v12, v70, 2, s2
	v_add3_u32 v18, v12, v71, v72
	v_lshlrev_b32_e32 v12, 16, v4
	v_and_b32_e32 v13, 0xffff0000, v4
	v_lshlrev_b32_e32 v14, 16, v5
	v_and_b32_e32 v15, 0xffff0000, v5
	ds_write_b128 v18, v[12:15]
	v_lshlrev_b32_e32 v12, 16, v6
	v_and_b32_e32 v13, 0xffff0000, v6
	v_lshlrev_b32_e32 v14, 16, v7
	v_and_b32_e32 v15, 0xffff0000, v7
	ds_write_b128 v18, v[12:15] offset:16
	v_lshl_add_u32 v12, v73, 2, s2
	v_add3_u32 v18, v12, v74, v75
	v_lshlrev_b32_e32 v12, 16, v8
	v_and_b32_e32 v13, 0xffff0000, v8
	v_lshlrev_b32_e32 v14, 16, v9
	v_and_b32_e32 v15, 0xffff0000, v9
	ds_write_b128 v18, v[12:15]
	v_lshlrev_b32_e32 v12, 16, v10
	v_and_b32_e32 v13, 0xffff0000, v10
	v_lshlrev_b32_e32 v14, 16, v11
	v_and_b32_e32 v15, 0xffff0000, v11
	ds_write_b128 v18, v[12:15] offset:16
	s_cmpk_gt_i32 s4, 0x7e
	s_cbranch_scc1 .Lrw_skipgl
	s_add_i32 s5, s4, 2
	s_lshl_b32 s5, s5, 4
	s_add_i32 s5, s5, s11
	v_add_u32_e32 v0, s5, v63
	v_add_u32_e32 v2, s5, v65
	v_add_u32_e32 v8, s5, v66
	v_mad_i64_i32 v[0:1], s[12:13], v0, s66, v[50:51]
	v_mad_i64_i32 v[4:5], s[12:13], v2, s66, v[52:53]
	v_mad_i64_i32 v[8:9], s[12:13], v8, s66, v[54:55]
	global_load_dwordx4 v[0:3], v[0:1], off
	global_load_dwordx4 v[4:7], v[4:5], off
	global_load_dwordx4 v[8:11], v[8:9], off
.Lrw_skipgl:
	s_waitcnt lgkmcnt(13)
	v_pk_mul_f32 v[176:177], v[60:61], v[138:139]
	v_pk_fma_f32 v[176:177], v[58:59], v[140:141], v[176:177]
	ds_read_b128 v[116:119], v78 offset:15616
	ds_read_b128 v[112:115], v78 offset:15360
	v_pk_fma_f32 v[180:181], v[60:61], v[134:135], v[60:61] neg_lo:[1,0,0] neg_hi:[1,0,0]
	v_add_f32_e32 v178, v176, v177
	v_pk_fma_f32 v[182:183], v[58:59], v[136:137], v[58:59] neg_lo:[1,0,0] neg_hi:[1,0,0]
	ds_read_b128 v[124:127], v78 offset:16128
	v_add_f32_dpp v178, v178, v178 quad_perm:[1,0,3,2] row_mask:0xf bank_mask:0xf bound_ctrl:1
	v_pk_fma_f32 v[180:181], v[146:147], v[152:153], v[180:181] op_sel_hi:[0,1,1]
	v_pk_fma_f32 v[182:183], v[146:147], v[154:155], v[182:183] op_sel_hi:[0,1,1]
	v_add_f32_dpp v178, v178, v178 quad_perm:[2,3,0,1] row_mask:0xf bank_mask:0xf bound_ctrl:1
	v_pk_mul_f32 v[184:185], v[60:61], v[128:129]
	v_pk_fma_f32 v[184:185], v[58:59], v[130:131], v[184:185]
	v_add_f32_dpp v178, v178, v178 row_half_mirror row_mask:0xf bank_mask:0xf bound_ctrl:1
	v_add_f32_e32 v167, v184, v185
	ds_read_b32 v132, v79 offset:16640
	v_add_f32_dpp v178, v178, v178 row_mirror row_mask:0xf bank_mask:0xf bound_ctrl:1
	ds_read_b128 v[120:123], v78 offset:15872
	ds_read_b128 v[128:131], v78 offset:16384
	v_pk_fma_f32 v[60:61], v[178:179], v[142:143], v[180:181] op_sel_hi:[0,1,1] neg_lo:[1,0,0] neg_hi:[1,0,0]
	v_pk_fma_f32 v[58:59], v[178:179], v[144:145], v[182:183] op_sel_hi:[0,1,1] neg_lo:[1,0,0] neg_hi:[1,0,0]
	s_waitcnt lgkmcnt(13)
	v_pk_mul_f32 v[176:177], v[60:61], v[94:95]
	v_pk_fma_f32 v[176:177], v[58:59], v[96:97], v[176:177]
	ds_read_b128 v[138:141], v78 offset:17152
	ds_read_b128 v[134:137], v78 offset:16896
	v_pk_fma_f32 v[180:181], v[60:61], v[90:91], v[60:61] neg_lo:[1,0,0] neg_hi:[1,0,0]
	v_add_f32_e32 v178, v176, v177
	v_pk_fma_f32 v[182:183], v[58:59], v[92:93], v[58:59] neg_lo:[1,0,0] neg_hi:[1,0,0]
	ds_read_b128 v[152:155], v78 offset:17664
	v_add_f32_dpp v178, v178, v178 quad_perm:[1,0,3,2] row_mask:0xf bank_mask:0xf bound_ctrl:1
	v_pk_fma_f32 v[180:181], v[110:111], v[102:103], v[180:181] op_sel_hi:[0,1,1]
	v_pk_fma_f32 v[182:183], v[110:111], v[104:105], v[182:183] op_sel_hi:[0,1,1]
	v_add_f32_dpp v178, v178, v178 quad_perm:[2,3,0,1] row_mask:0xf bank_mask:0xf bound_ctrl:1
	v_pk_mul_f32 v[184:185], v[60:61], v[156:157]
	v_pk_fma_f32 v[184:185], v[58:59], v[158:159], v[184:185]
	v_add_f32_dpp v178, v178, v178 row_half_mirror row_mask:0xf bank_mask:0xf bound_ctrl:1
	v_add_f32_e32 v168, v184, v185
	ds_read_b32 v146, v79 offset:18176
	v_add_f32_dpp v178, v178, v178 row_mirror row_mask:0xf bank_mask:0xf bound_ctrl:1
	ds_read_b128 v[142:145], v78 offset:17408
	ds_read_b128 v[156:159], v78 offset:17920
	v_pk_fma_f32 v[60:61], v[178:179], v[98:99], v[180:181] op_sel_hi:[0,1,1] neg_lo:[1,0,0] neg_hi:[1,0,0]
	v_pk_fma_f32 v[58:59], v[178:179], v[100:101], v[182:183] op_sel_hi:[0,1,1] neg_lo:[1,0,0] neg_hi:[1,0,0]
	s_waitcnt lgkmcnt(7)
	v_pk_mul_f32 v[176:177], v[60:61], v[116:117]
	v_pk_fma_f32 v[176:177], v[58:59], v[118:119], v[176:177]
	ds_read_b128 v[94:97], v78 offset:18688
	ds_read_b128 v[90:93], v78 offset:18432
	v_pk_fma_f32 v[180:181], v[60:61], v[112:113], v[60:61] neg_lo:[1,0,0] neg_hi:[1,0,0]
	v_add_f32_e32 v178, v176, v177
	v_pk_fma_f32 v[182:183], v[58:59], v[114:115], v[58:59] neg_lo:[1,0,0] neg_hi:[1,0,0]
	ds_read_b128 v[102:105], v78 offset:19200
	v_add_f32_dpp v178, v178, v178 quad_perm:[1,0,3,2] row_mask:0xf bank_mask:0xf bound_ctrl:1
	v_pk_fma_f32 v[180:181], v[132:133], v[124:125], v[180:181] op_sel_hi:[0,1,1]
	v_pk_fma_f32 v[182:183], v[132:133], v[126:127], v[182:183] op_sel_hi:[0,1,1]
	v_add_f32_dpp v178, v178, v178 quad_perm:[2,3,0,1] row_mask:0xf bank_mask:0xf bound_ctrl:1
	v_pk_mul_f32 v[184:185], v[60:61], v[106:107]
	v_pk_fma_f32 v[184:185], v[58:59], v[108:109], v[184:185]
	v_add_f32_dpp v178, v178, v178 row_half_mirror row_mask:0xf bank_mask:0xf bound_ctrl:1
	v_add_f32_e32 v169, v184, v185
	ds_read_b32 v110, v79 offset:19712
	v_add_f32_dpp v178, v178, v178 row_mirror row_mask:0xf bank_mask:0xf bound_ctrl:1
	ds_read_b128 v[98:101], v78 offset:18944
	ds_read_b128 v[106:109], v78 offset:19456
	v_pk_fma_f32 v[60:61], v[178:179], v[120:121], v[180:181] op_sel_hi:[0,1,1] neg_lo:[1,0,0] neg_hi:[1,0,0]
	v_pk_fma_f32 v[58:59], v[178:179], v[122:123], v[182:183] op_sel_hi:[0,1,1] neg_lo:[1,0,0] neg_hi:[1,0,0]
	s_waitcnt lgkmcnt(7)
; __device__ __forceinline__ void rwkv_scan_unit(CP p, int u, char* smem) {
;     ...
;     for (int s = 0; s < 16; ++s) {
;       const float* sb = cb + (s + 1) * 384;
;       const float4 om_n = *reinterpret_cast<const float4*>(sb + j * 4);
;       const float4 kk_n = *reinterpret_cast<const float4*>(sb + 64 + j * 4);
;       const float4 bb_n = *reinterpret_cast<const float4*>(sb + 128 + j * 4);
;       const float4 kp_n = *reinterpret_cast<const float4*>(sb + 192 + j * 4);
;       const float4 rr_n = *reinterpret_cast<const float4*>(sb + 256 + j * 4);
;       const float vv_n = sb[320 + rowv];
;       __builtin_amdgcn_sched_barrier(0);
;       float d = s0 * kk.x + s1 * kk.y + s2 * kk.z + s3 * kk.w;
;       d = allreduce16(d);
;       const float sa = -d;
;       s0 = fmaf(-s0, om.x, s0); s1 = fmaf(-s1, om.y, s1); s2 = fmaf(-s2, om.z, s2); s3 = fmaf(-s3, om.w, s3);
;       s0 = fmaf(sa, bb.x, s0); s1 = fmaf(sa, bb.y, s1); s2 = fmaf(sa, bb.z, s2); s3 = fmaf(sa, bb.w, s3);
;       s0 = fmaf(vv, kp.x, s0); s1 = fmaf(vv, kp.y, s1); s2 = fmaf(vv, kp.z, s2); s3 = fmaf(vv, kp.w, s3);
;       float y = s0 * rr.x + s1 * rr.y + s2 * rr.z + s3 * rr.w;
;       y = allreduce16(y);
;       if (j == s) ykeep = y;
;       om = om_n; kk = kk_n; bb = bb_n; kp = kp_n; rr = rr_n; vv = vv_n;
;     }
	v_pk_mul_f32 v[176:177], v[60:61], v[138:139]
	v_pk_fma_f32 v[176:177], v[58:59], v[140:141], v[176:177]
	ds_read_b128 v[116:119], v78 offset:20224
	ds_read_b128 v[112:115], v78 offset:19968
	v_pk_fma_f32 v[180:181], v[60:61], v[134:135], v[60:61] neg_lo:[1,0,0] neg_hi:[1,0,0]
	v_add_f32_e32 v178, v176, v177
	v_pk_fma_f32 v[182:183], v[58:59], v[136:137], v[58:59] neg_lo:[1,0,0] neg_hi:[1,0,0]
	ds_read_b128 v[124:127], v78 offset:20736
	v_add_f32_dpp v178, v178, v178 quad_perm:[1,0,3,2] row_mask:0xf bank_mask:0xf bound_ctrl:1
	v_pk_fma_f32 v[180:181], v[146:147], v[152:153], v[180:181] op_sel_hi:[0,1,1]
	v_pk_fma_f32 v[182:183], v[146:147], v[154:155], v[182:183] op_sel_hi:[0,1,1]
	v_add_f32_dpp v178, v178, v178 quad_perm:[2,3,0,1] row_mask:0xf bank_mask:0xf bound_ctrl:1
	v_pk_mul_f32 v[184:185], v[60:61], v[128:129]
	v_pk_fma_f32 v[184:185], v[58:59], v[130:131], v[184:185]
	v_add_f32_dpp v178, v178, v178 row_half_mirror row_mask:0xf bank_mask:0xf bound_ctrl:1
	v_add_f32_e32 v170, v184, v185
	ds_read_b32 v132, v79 offset:21248
	v_add_f32_dpp v178, v178, v178 row_mirror row_mask:0xf bank_mask:0xf bound_ctrl:1
	ds_read_b128 v[120:123], v78 offset:20480
	ds_read_b128 v[128:131], v78 offset:20992
	v_pk_fma_f32 v[60:61], v[178:179], v[142:143], v[180:181] op_sel_hi:[0,1,1] neg_lo:[1,0,0] neg_hi:[1,0,0]
	v_pk_fma_f32 v[58:59], v[178:179], v[144:145], v[182:183] op_sel_hi:[0,1,1] neg_lo:[1,0,0] neg_hi:[1,0,0]
	s_waitcnt lgkmcnt(7)
	v_pk_mul_f32 v[176:177], v[60:61], v[94:95]
	v_pk_fma_f32 v[176:177], v[58:59], v[96:97], v[176:177]
	ds_read_b128 v[138:141], v78 offset:21760
	ds_read_b128 v[134:137], v78 offset:21504
	v_pk_fma_f32 v[180:181], v[60:61], v[90:91], v[60:61] neg_lo:[1,0,0] neg_hi:[1,0,0]
	v_add_f32_e32 v178, v176, v177
	v_pk_fma_f32 v[182:183], v[58:59], v[92:93], v[58:59] neg_lo:[1,0,0] neg_hi:[1,0,0]
	ds_read_b128 v[152:155], v78 offset:22272
	v_add_f32_dpp v178, v178, v178 quad_perm:[1,0,3,2] row_mask:0xf bank_mask:0xf bound_ctrl:1
	v_pk_fma_f32 v[180:181], v[110:111], v[102:103], v[180:181] op_sel_hi:[0,1,1]
	v_pk_fma_f32 v[182:183], v[110:111], v[104:105], v[182:183] op_sel_hi:[0,1,1]
	v_add_f32_dpp v178, v178, v178 quad_perm:[2,3,0,1] row_mask:0xf bank_mask:0xf bound_ctrl:1
	v_pk_mul_f32 v[184:185], v[60:61], v[156:157]
	v_pk_fma_f32 v[184:185], v[58:59], v[158:159], v[184:185]
	v_add_f32_dpp v178, v178, v178 row_half_mirror row_mask:0xf bank_mask:0xf bound_ctrl:1
	v_add_f32_e32 v171, v184, v185
	ds_read_b32 v146, v79 offset:22784
	v_add_f32_dpp v178, v178, v178 row_mirror row_mask:0xf bank_mask:0xf bound_ctrl:1
	ds_read_b128 v[142:145], v78 offset:22016
	ds_read_b128 v[156:159], v78 offset:22528
	v_pk_fma_f32 v[60:61], v[178:179], v[98:99], v[180:181] op_sel_hi:[0,1,1] neg_lo:[1,0,0] neg_hi:[1,0,0]
	v_pk_fma_f32 v[58:59], v[178:179], v[100:101], v[182:183] op_sel_hi:[0,1,1] neg_lo:[1,0,0] neg_hi:[1,0,0]
	s_waitcnt lgkmcnt(7)
	v_pk_mul_f32 v[176:177], v[60:61], v[116:117]
	v_pk_fma_f32 v[176:177], v[58:59], v[118:119], v[176:177]
	ds_read_b128 v[94:97], v78 offset:23296
	ds_read_b128 v[90:93], v78 offset:23040
	v_pk_fma_f32 v[180:181], v[60:61], v[112:113], v[60:61] neg_lo:[1,0,0] neg_hi:[1,0,0]
	v_add_f32_e32 v178, v176, v177
	v_pk_fma_f32 v[182:183], v[58:59], v[114:115], v[58:59] neg_lo:[1,0,0] neg_hi:[1,0,0]
	ds_read_b128 v[102:105], v78 offset:23808
	v_add_f32_dpp v178, v178, v178 quad_perm:[1,0,3,2] row_mask:0xf bank_mask:0xf bound_ctrl:1
	v_pk_fma_f32 v[180:181], v[132:133], v[124:125], v[180:181] op_sel_hi:[0,1,1]
	v_pk_fma_f32 v[182:183], v[132:133], v[126:127], v[182:183] op_sel_hi:[0,1,1]
	v_add_f32_dpp v178, v178, v178 quad_perm:[2,3,0,1] row_mask:0xf bank_mask:0xf bound_ctrl:1
	v_pk_mul_f32 v[184:185], v[60:61], v[106:107]
	v_pk_fma_f32 v[184:185], v[58:59], v[108:109], v[184:185]
	v_add_f32_dpp v178, v178, v178 row_half_mirror row_mask:0xf bank_mask:0xf bound_ctrl:1
	v_add_f32_e32 v172, v184, v185
	ds_read_b32 v110, v79 offset:24320
	v_add_f32_dpp v178, v178, v178 row_mirror row_mask:0xf bank_mask:0xf bound_ctrl:1
	ds_read_b128 v[98:101], v78 offset:23552
	ds_read_b128 v[106:109], v78 offset:24064
	v_pk_fma_f32 v[60:61], v[178:179], v[120:121], v[180:181] op_sel_hi:[0,1,1] neg_lo:[1,0,0] neg_hi:[1,0,0]
	v_pk_fma_f32 v[58:59], v[178:179], v[122:123], v[182:183] op_sel_hi:[0,1,1] neg_lo:[1,0,0] neg_hi:[1,0,0]
	s_waitcnt lgkmcnt(7)
	v_pk_mul_f32 v[176:177], v[60:61], v[138:139]
	v_pk_fma_f32 v[176:177], v[58:59], v[140:141], v[176:177]
	v_pk_fma_f32 v[180:181], v[60:61], v[134:135], v[60:61] neg_lo:[1,0,0] neg_hi:[1,0,0]
	v_add_f32_e32 v178, v176, v177
	v_pk_fma_f32 v[182:183], v[58:59], v[136:137], v[58:59] neg_lo:[1,0,0] neg_hi:[1,0,0]
	s_nop 0
	v_add_f32_dpp v178, v178, v178 quad_perm:[1,0,3,2] row_mask:0xf bank_mask:0xf bound_ctrl:1
	v_pk_fma_f32 v[180:181], v[146:147], v[152:153], v[180:181] op_sel_hi:[0,1,1]
	v_pk_fma_f32 v[182:183], v[146:147], v[154:155], v[182:183] op_sel_hi:[0,1,1]
	v_add_f32_dpp v178, v178, v178 quad_perm:[2,3,0,1] row_mask:0xf bank_mask:0xf bound_ctrl:1
	v_pk_mul_f32 v[184:185], v[60:61], v[128:129]
	v_pk_fma_f32 v[184:185], v[58:59], v[130:131], v[184:185]
	v_add_f32_dpp v178, v178, v178 row_half_mirror row_mask:0xf bank_mask:0xf bound_ctrl:1
	v_add_f32_e32 v173, v184, v185
	s_nop 0
	v_add_f32_dpp v178, v178, v178 row_mirror row_mask:0xf bank_mask:0xf bound_ctrl:1
	v_pk_fma_f32 v[60:61], v[178:179], v[142:143], v[180:181] op_sel_hi:[0,1,1] neg_lo:[1,0,0] neg_hi:[1,0,0]
	v_pk_fma_f32 v[58:59], v[178:179], v[144:145], v[182:183] op_sel_hi:[0,1,1] neg_lo:[1,0,0] neg_hi:[1,0,0]
	s_waitcnt lgkmcnt(1)
; __device__ __forceinline__ bf16_t f2bf(float f) { return (bf16_t)(pack2(f, 0.f) & 0xffffu); }
; __device__ __forceinline__ void rwkv_scan_unit(CP p, int u, char* smem) {
;     ...
;       float y = s0 * rr.x + s1 * rr.y + s2 * rr.z + s3 * rr.w;
;       y = allreduce16(y);
;       if (j == s) ykeep = y;
;       om = om_n; kk = kk_n; bb = bb_n; kp = kp_n; rr = rr_n; vv = vv_n;
;     }
;     Y[(size_t)(rowof(b, c * 16) + j) * 1024 + 256 + h * 64 + rowv] = f2bf(ykeep);
;     if (c + 1 < NCH) lwrite((c + 1) & 1);
;     half_barrier(smem);
	v_pk_mul_f32 v[176:177], v[60:61], v[94:95]
	v_pk_fma_f32 v[176:177], v[58:59], v[96:97], v[176:177]
	v_pk_fma_f32 v[180:181], v[60:61], v[90:91], v[60:61] neg_lo:[1,0,0] neg_hi:[1,0,0]
	v_add_f32_e32 v178, v176, v177
	v_pk_fma_f32 v[182:183], v[58:59], v[92:93], v[58:59] neg_lo:[1,0,0] neg_hi:[1,0,0]
	s_nop 0
	v_add_f32_dpp v178, v178, v178 quad_perm:[1,0,3,2] row_mask:0xf bank_mask:0xf bound_ctrl:1
	v_pk_fma_f32 v[180:181], v[110:111], v[102:103], v[180:181] op_sel_hi:[0,1,1]
	v_pk_fma_f32 v[182:183], v[110:111], v[104:105], v[182:183] op_sel_hi:[0,1,1]
	v_add_f32_dpp v178, v178, v178 quad_perm:[2,3,0,1] row_mask:0xf bank_mask:0xf bound_ctrl:1
	v_pk_mul_f32 v[184:185], v[60:61], v[156:157]
	v_pk_fma_f32 v[184:185], v[58:59], v[158:159], v[184:185]
	v_add_f32_dpp v178, v178, v178 row_half_mirror row_mask:0xf bank_mask:0xf bound_ctrl:1
	v_add_f32_e32 v174, v184, v185
	s_nop 0
	v_add_f32_dpp v178, v178, v178 row_mirror row_mask:0xf bank_mask:0xf bound_ctrl:1
	v_pk_fma_f32 v[60:61], v[178:179], v[98:99], v[180:181] op_sel_hi:[0,1,1] neg_lo:[1,0,0] neg_hi:[1,0,0]
	v_pk_fma_f32 v[58:59], v[178:179], v[100:101], v[182:183] op_sel_hi:[0,1,1] neg_lo:[1,0,0] neg_hi:[1,0,0]
	s_waitcnt lgkmcnt(0)
	v_pk_mul_f32 v[184:185], v[60:61], v[106:107]
	v_pk_fma_f32 v[184:185], v[58:59], v[108:109], v[184:185]
	v_add_f32_e32 v175, v184, v185
	v_add_f32_dpp v160, v160, v160 row_ror:8 row_mask:0xf bank_mask:0x3 bound_ctrl:1
	v_add_f32_dpp v161, v161, v161 row_ror:8 row_mask:0xf bank_mask:0x3 bound_ctrl:1
	v_add_f32_dpp v162, v162, v162 row_ror:8 row_mask:0xf bank_mask:0x3 bound_ctrl:1
	v_add_f32_dpp v163, v163, v163 row_ror:8 row_mask:0xf bank_mask:0x3 bound_ctrl:1
	v_add_f32_dpp v164, v164, v164 row_ror:8 row_mask:0xf bank_mask:0x3 bound_ctrl:1
	v_add_f32_dpp v165, v165, v165 row_ror:8 row_mask:0xf bank_mask:0x3 bound_ctrl:1
	v_add_f32_dpp v166, v166, v166 row_ror:8 row_mask:0xf bank_mask:0x3 bound_ctrl:1
	v_add_f32_dpp v167, v167, v167 row_ror:8 row_mask:0xf bank_mask:0x3 bound_ctrl:1
	v_add_f32_dpp v160, v168, v168 row_ror:8 row_mask:0xf bank_mask:0xc bound_ctrl:1
	v_add_f32_dpp v161, v169, v169 row_ror:8 row_mask:0xf bank_mask:0xc bound_ctrl:1
	v_add_f32_dpp v162, v170, v170 row_ror:8 row_mask:0xf bank_mask:0xc bound_ctrl:1
	v_add_f32_dpp v163, v171, v171 row_ror:8 row_mask:0xf bank_mask:0xc bound_ctrl:1
	v_add_f32_dpp v164, v172, v172 row_ror:8 row_mask:0xf bank_mask:0xc bound_ctrl:1
	v_add_f32_dpp v165, v173, v173 row_ror:8 row_mask:0xf bank_mask:0xc bound_ctrl:1
	v_add_f32_dpp v166, v174, v174 row_ror:8 row_mask:0xf bank_mask:0xc bound_ctrl:1
	v_add_f32_dpp v167, v175, v175 row_ror:8 row_mask:0xf bank_mask:0xc bound_ctrl:1
	v_add_f32_dpp v160, v160, v160 row_half_mirror row_mask:0xf bank_mask:0x5 bound_ctrl:1
	v_add_f32_dpp v161, v161, v161 row_half_mirror row_mask:0xf bank_mask:0x5 bound_ctrl:1
	v_add_f32_dpp v162, v162, v162 row_half_mirror row_mask:0xf bank_mask:0x5 bound_ctrl:1
	v_add_f32_dpp v163, v163, v163 row_half_mirror row_mask:0xf bank_mask:0x5 bound_ctrl:1
	v_add_f32_dpp v160, v164, v164 row_half_mirror row_mask:0xf bank_mask:0xa bound_ctrl:1
	v_add_f32_dpp v161, v165, v165 row_half_mirror row_mask:0xf bank_mask:0xa bound_ctrl:1
	v_add_f32_dpp v162, v166, v166 row_half_mirror row_mask:0xf bank_mask:0xa bound_ctrl:1
	v_add_f32_dpp v163, v167, v167 row_half_mirror row_mask:0xf bank_mask:0xa bound_ctrl:1
	v_and_b32_e32 v186, 2, v76
	v_cmp_ne_u32_e32 vcc, 0, v186
	v_and_b32_e32 v186, 1, v76
	s_nop 0
	v_cndmask_b32_e32 v187, v160, v162, vcc
	v_cndmask_b32_e32 v188, v162, v160, vcc
	v_cndmask_b32_e32 v189, v161, v163, vcc
	v_cndmask_b32_e32 v190, v163, v161, vcc
	v_cmp_ne_u32_e32 vcc, 0, v186
	v_add_f32_dpp v160, v188, v187 quad_perm:[2,3,0,1] row_mask:0xf bank_mask:0xf bound_ctrl:1
	v_add_f32_dpp v161, v190, v189 quad_perm:[2,3,0,1] row_mask:0xf bank_mask:0xf bound_ctrl:1
	v_cndmask_b32_e32 v187, v160, v161, vcc
	v_cndmask_b32_e32 v188, v161, v160, vcc
	s_nop 1
	v_add_f32_dpp v82, v188, v187 quad_perm:[1,0,3,2] row_mask:0xf bank_mask:0xf bound_ctrl:1
	s_lshl_b32 s5, s4, 4
	s_add_i32 s5, s5, s11
	s_cmp_eq_u32 s4, 0
	s_cselect_b32 s5, s10, s5
	v_or_b32_e32 v12, s5, v76
	v_ashrrev_i32_e32 v13, 31, v12
	v_lshlrev_b64 v[12:13], 11, v[12:13]
	v_cvt_pk_bf16_f32 v14, v82, s0
	v_lshl_add_u64 v[12:13], v[56:57], 0, v[12:13]
	global_store_short v[12:13], v14, off
	s_waitcnt lgkmcnt(0)
	s_mov_b64 s[12:13], exec
	s_mov_b64 exec, 1
	ds_add_u32 v193, v195 offset:8
	s_mov_b64 exec, s[12:13]
	v_add_u32_e32 v194, 4, v194
